# differential attention tile loop reordered to P.V(t-1) first, then QK^T, max, softmax: no P copy registers, rescale-only rare path
# baseline (speedup 1.0000x reference)
; #define LAS __attribute__((address_space(3)))
; template <int MODE>
; __device__ __forceinline__ void attn_unit(const Params& p, int layer, LAS unsigned char* lds, int b, int hsel, int qb, bool ctxq) {
;     ...
;     auto commit = [&](int bufi) {
;         LAS unsigned char* bp = lds + bufi * AT_BUF + lrow * AT_PITCH + lch * 16;
;         if (MODE == 1) { *(LAS u32x4*)bp = treg[0]; *(LAS u32x4*)(bp + 128 * AT_PITCH) = treg[1]; }
;         else { *(LAS u32x4*)bp = treg[0]; *(LAS u32x4*)(bp + 64 * AT_PITCH) = treg[1]; *(LAS u32x4*)(bp + 128 * AT_PITCH) = treg[2]; *(LAS u32x4*)(bp + 192 * AT_PITCH) = treg[NBATCH - 1]; }
;     ...
;     for (int t = 0; t < ntile; ++t) {
;         const int bnext = bcur == 2 ? 0 : bcur + 1;
;         if (t + 1 < ntile) commit(bnext);
.LBB0_646:
	s_mov_b32 s13, s3
	s_add_i32 s3, s3, 1
	s_cmp_lg_u32 s13, 2
	s_cselect_b32 s3, s3, 0
	s_branch .Lat0_bodyB
.Lat0_bodyB:
	s_cmpk_gt_u32 s12, 0x82
	s_cbranch_scc1 .Lat0_B648
	s_mul_i32 s14, s3, 0xa000
	v_add_u32_e32 v114, s14, v197
	s_waitcnt vmcnt(2)
	ds_write_b128 v114, v[18:21]
	s_waitcnt vmcnt(1)
	ds_write_b128 v114, v[22:25] offset:10240
	s_waitcnt vmcnt(0)
	ds_write_b128 v114, v[26:29] offset:20480
	ds_write_b128 v114, v[30:33] offset:30720

; #define LAS __attribute__((address_space(3)))
; #define MFMA16(a, b, c) __builtin_amdgcn_mfma_f32_16x16x32_bf16((a), (b), (c), 0, 0, 0)
; template <int NS, int DV, class MaskF> ...
;     ...
; #pragma unroll
;     for (int st = 0; st < NS; ++st)
; #pragma unroll
;         for (int kt = 0; kt < 4; ++kt) {
;             const LAS unsigned char* kp = bufK + (kslot[st] * 64 + kt * 16 + fr) * AT_PITCH + g * 16;
;             const bf16x8 a0 = *(const LAS bf16x8*)kp, a1 = *(const LAS bf16x8*)(kp + 64);
;             const float nm = -mrun[st];
;             f32x4 z = {nm, nm, nm, nm};
;             z = MFMA16(a0, qf[st][0], z); z = MFMA16(a1, qf[st][1], z);
;             s[st][kt] = z;
;         }
;     ...
;         for (int dt = 0; dt < DV / 16; ++dt)
; #pragma unroll
;             for (int j = 0; j < 2; ++j) {
;                 const bf16x8 va = *(const LAS bf16x8*)(bufV + (128 + vrow0 + dt * 16 + fr) * AT_PITCH + (j * 32 + g * 8) * 2);
; #pragma unroll
;                 for (int st = 0; st < NS; ++st) o[st][dt] = MFMA16(va, pkp[st][j], o[st][dt]);
;             }
.Lat0_B650:
	s_mul_i32 s15, s15, 0xa000
	s_add_i32 s15, s15, 0
	v_add3_u32 v179, s15, v226, v0
	v_add3_u32 v180, s15, v225, v0
	v_add3_u32 v178, s15, v224, v0
	ds_read_b128 v[130:133], v179 offset:20480
	ds_read_b128 v[134:137], v179 offset:20544
	ds_read_b128 v[138:141], v179 offset:23040
	ds_read_b128 v[142:145], v179 offset:23104
	ds_read_b128 v[114:117], v179 offset:25600
	ds_read_b128 v[118:121], v179 offset:25664
	ds_read_b128 v[122:125], v180 offset:20480
	ds_read_b128 v[126:129], v180 offset:20544
	s_waitcnt lgkmcnt(7)
	v_mfma_f32_16x16x32_bf16 v[38:41], v[130:133], v[54:57], v[38:41]
	v_mfma_f32_16x16x32_bf16 v[78:81], v[130:133], v[98:101], v[78:81]
	ds_read_b128 v[130:133], v179 offset:30720
	s_waitcnt lgkmcnt(7)
	v_mfma_f32_16x16x32_bf16 v[38:41], v[134:137], v[46:49], v[38:41]
	v_mfma_f32_16x16x32_bf16 v[78:81], v[134:137], v[70:73], v[78:81]
	ds_read_b128 v[134:137], v179 offset:30784
	s_waitcnt lgkmcnt(7)
	v_mfma_f32_16x16x32_bf16 v[34:37], v[138:141], v[54:57], v[34:37]
	v_mfma_f32_16x16x32_bf16 v[74:77], v[138:141], v[98:101], v[74:77]
	ds_read_b128 v[138:141], v179 offset:33280
	s_waitcnt lgkmcnt(7)
	v_mfma_f32_16x16x32_bf16 v[34:37], v[142:145], v[46:49], v[34:37]
	v_mfma_f32_16x16x32_bf16 v[74:77], v[142:145], v[70:73], v[74:77]
	ds_read_b128 v[142:145], v179 offset:33344
	s_waitcnt lgkmcnt(7)
	v_mfma_f32_16x16x32_bf16 v[42:45], v[114:117], v[54:57], v[42:45]
	v_mfma_f32_16x16x32_bf16 v[82:85], v[114:117], v[98:101], v[82:85]
	ds_read_b128 v[114:117], v179 offset:35840
	s_waitcnt lgkmcnt(7)
	v_mfma_f32_16x16x32_bf16 v[42:45], v[118:121], v[46:49], v[42:45]
	v_mfma_f32_16x16x32_bf16 v[82:85], v[118:121], v[70:73], v[82:85]
	ds_read_b128 v[118:121], v179 offset:35904
	s_waitcnt lgkmcnt(7)
	v_mfma_f32_16x16x32_bf16 v[50:53], v[122:125], v[54:57], v[50:53]
	v_mfma_f32_16x16x32_bf16 v[86:89], v[122:125], v[98:101], v[86:89]
	ds_read_b128 v[122:125], v178 offset:20480
	s_waitcnt lgkmcnt(7)
	v_mfma_f32_16x16x32_bf16 v[50:53], v[126:129], v[46:49], v[50:53]
	v_mfma_f32_16x16x32_bf16 v[86:89], v[126:129], v[70:73], v[86:89]
	ds_read_b128 v[126:129], v178 offset:20544
	s_waitcnt lgkmcnt(7)
	v_mfma_f32_16x16x32_bf16 v[62:65], v[130:133], v[54:57], v[62:65]
	v_mfma_f32_16x16x32_bf16 v[94:97], v[130:133], v[98:101], v[94:97]
	s_waitcnt lgkmcnt(6)
	v_mfma_f32_16x16x32_bf16 v[62:65], v[134:137], v[46:49], v[62:65]
	v_mfma_f32_16x16x32_bf16 v[94:97], v[134:137], v[70:73], v[94:97]
	s_waitcnt lgkmcnt(5)
	v_mfma_f32_16x16x32_bf16 v[58:61], v[138:141], v[54:57], v[58:61]
	v_mfma_f32_16x16x32_bf16 v[90:93], v[138:141], v[98:101], v[90:93]
	s_waitcnt lgkmcnt(4)
	v_mfma_f32_16x16x32_bf16 v[58:61], v[142:145], v[46:49], v[58:61]
	v_mfma_f32_16x16x32_bf16 v[90:93], v[142:145], v[70:73], v[90:93]
	s_waitcnt lgkmcnt(3)
	v_mfma_f32_16x16x32_bf16 v[66:69], v[114:117], v[54:57], v[66:69]
	v_mfma_f32_16x16x32_bf16 v[102:105], v[114:117], v[98:101], v[102:105]
	s_waitcnt lgkmcnt(2)
	v_mfma_f32_16x16x32_bf16 v[66:69], v[118:121], v[46:49], v[66:69]
	v_mfma_f32_16x16x32_bf16 v[102:105], v[118:121], v[70:73], v[102:105]
	s_waitcnt lgkmcnt(1)
	v_mfma_f32_16x16x32_bf16 v[106:109], v[122:125], v[54:57], v[106:109]
	v_mfma_f32_16x16x32_bf16 v[110:113], v[122:125], v[98:101], v[110:113]
	s_waitcnt lgkmcnt(0)
	v_mfma_f32_16x16x32_bf16 v[106:109], v[126:129], v[46:49], v[106:109]
	v_mfma_f32_16x16x32_bf16 v[110:113], v[126:129], v[70:73], v[110:113]
	s_mul_i32 s14, s13, 0xa000
	v_add_u32_e32 v190, s14, v227
	ds_read_b128 v[146:149], v190
	ds_read_b128 v[150:153], v190 offset:64
	ds_read_b128 v[154:157], v190 offset:2560
	ds_read_b128 v[158:161], v190 offset:2624
	ds_read_b128 v[182:185], v190 offset:5120
	ds_read_b128 v[186:189], v190 offset:5184
	v_xor_b32_e32 v126, 0x80000000, v173
	v_xor_b32_e32 v138, 0x80000000, v172
	v_mov_b32_e32 v127, v126
	v_mov_b32_e32 v128, v126
	v_mov_b32_e32 v129, v126
	v_mov_b32_e32 v139, v138
	v_mov_b32_e32 v140, v138
	v_mov_b32_e32 v141, v138
	s_waitcnt lgkmcnt(5)
	v_mfma_f32_16x16x32_bf16 v[114:117], v[146:149], v[2:5], v[126:129]
	ds_read_b128 v[146:149], v190 offset:7680
	s_waitcnt lgkmcnt(5)
	v_mfma_f32_16x16x32_bf16 v[114:117], v[150:153], v[6:9], v[114:117]
	ds_read_b128 v[150:153], v190 offset:7744
	s_waitcnt lgkmcnt(5)
	v_mfma_f32_16x16x32_bf16 v[118:121], v[154:157], v[2:5], v[126:129]
	ds_read_b128 v[154:157], v190 offset:10240
	s_waitcnt lgkmcnt(5)
	v_mfma_f32_16x16x32_bf16 v[118:121], v[158:161], v[6:9], v[118:121]
	ds_read_b128 v[158:161], v190 offset:10304
	s_waitcnt lgkmcnt(5)
	v_mfma_f32_16x16x32_bf16 v[122:125], v[182:185], v[2:5], v[126:129]
	ds_read_b128 v[182:185], v190 offset:12800
	s_waitcnt lgkmcnt(5)
	v_mfma_f32_16x16x32_bf16 v[122:125], v[186:189], v[6:9], v[122:125]
	ds_read_b128 v[186:189], v190 offset:12864
	s_waitcnt lgkmcnt(5)
	v_mfma_f32_16x16x32_bf16 v[126:129], v[146:149], v[2:5], v[126:129]
	ds_read_b128 v[146:149], v190 offset:15360
	s_waitcnt lgkmcnt(5)
	v_mfma_f32_16x16x32_bf16 v[126:129], v[150:153], v[6:9], v[126:129]
	ds_read_b128 v[150:153], v190 offset:15424
	s_waitcnt lgkmcnt(5)
	v_mfma_f32_16x16x32_bf16 v[134:137], v[154:157], v[10:13], v[138:141]
	ds_read_b128 v[154:157], v190 offset:17920
	s_waitcnt lgkmcnt(5)
	v_mfma_f32_16x16x32_bf16 v[134:137], v[158:161], v[14:17], v[134:137]
	ds_read_b128 v[158:161], v190 offset:17984
	s_waitcnt lgkmcnt(5)
	v_mfma_f32_16x16x32_bf16 v[142:145], v[182:185], v[10:13], v[138:141]
	s_waitcnt lgkmcnt(4)
	v_mfma_f32_16x16x32_bf16 v[142:145], v[186:189], v[14:17], v[142:145]
	s_waitcnt lgkmcnt(3)
	v_mfma_f32_16x16x32_bf16 v[130:133], v[146:149], v[10:13], v[138:141]
	s_waitcnt lgkmcnt(2)
	v_mfma_f32_16x16x32_bf16 v[130:133], v[150:153], v[14:17], v[130:133]
	s_waitcnt lgkmcnt(1)
; #define LAS __attribute__((address_space(3)))
; __device__ __forceinline__ float ex2(float x) { return __builtin_amdgcn_exp2f(x); }
; __device__ __forceinline__ float max3f(float a, float b, float c) { float r; asm("v_max3_f32 %0, %1, %2, %3" : "=v"(r) : "v"(a), "v"(b), "v"(c)); return r; }
; #define MFMA16(a, b, c) __builtin_amdgcn_mfma_f32_16x16x32_bf16((a), (b), (c), 0, 0, 0)
; template <int NS, int DV, class MaskF> ...
;     ...
;         float mx = max3f(s[st][0][0], s[st][0][1], s[st][0][2]);
;         mx = max3f(mx, s[st][0][3], s[st][1][0]); mx = max3f(mx, s[st][1][1], s[st][1][2]); mx = max3f(mx, s[st][1][3], s[st][2][0]);
;         mx = max3f(mx, s[st][2][1], s[st][2][2]); mx = max3f(mx, s[st][2][3], s[st][3][0]); mx = max3f(mx, s[st][3][1], s[st][3][2]); mx = max3f(mx, s[st][3][3], mx);
;         mx = max3f(mx, __shfl_xor(mx, 16), mx); mx = max3f(mx, __shfl_xor(mx, 32), mx);
;         mxs[st] = mx; slow = slow || (mx > 8.0f);
;     }
;     if (__any(slow)) {
; #pragma unroll
;         for (int dt = 0; dt < DV / 16; ++dt)
; #pragma unroll
;             for (int j = 0; j < 2; ++j) {
;                 const bf16x8 va = *(const LAS bf16x8*)(bufV + (128 + vrow0 + dt * 16 + fr) * AT_PITCH + (j * 32 + g * 8) * 2);
; #pragma unroll
;                 for (int st = 0; st < NS; ++st) o[st][dt] = MFMA16(va, pkp[st][j], o[st][dt]);
;             }
; #pragma unroll
;         for (int st = 0; st < NS; ++st) {
;             const float d = mxs[st] < -1e20f ? 0.f : (first ? mxs[st] : fmaxf(mxs[st], 0.f));
;             mrun[st] += d; const float alpha = ex2(-d);
;             lrun[st] *= alpha;
; #pragma unroll
;             for (int kt = 0; kt < 4; ++kt) s[st][kt] = s[st][kt] - d;
; #pragma unroll
;             for (int dt = 0; dt < DV / 16; ++dt) o[st][dt] = o[st][dt] * alpha;
;             pkp[st][0] = (bf16x8){0, 0, 0, 0, 0, 0, 0, 0}; pkp[st][1] = pkp[st][0];
;         }
;     }
	v_mfma_f32_16x16x32_bf16 v[138:141], v[154:157], v[10:13], v[138:141]
	s_waitcnt lgkmcnt(0)
	v_mfma_f32_16x16x32_bf16 v[138:141], v[158:161], v[14:17], v[138:141]
	v_max3_f32 v146, v114, v115, v116
	v_max3_f32 v148, v134, v135, v136
	s_mov_b32 s16, 0x41000000
	v_max3_f32 v146, v146, v117, v118
	v_max3_f32 v148, v148, v137, v142
	v_add3_u32 v179, s15, v226, v0
	v_max3_f32 v146, v146, v119, v120
	v_max3_f32 v148, v148, v143, v144
	v_add3_u32 v180, s15, v225, v0
	v_max3_f32 v146, v146, v121, v122
	v_max3_f32 v148, v148, v145, v130
	v_add3_u32 v178, s15, v224, v0
	v_max3_f32 v146, v146, v123, v124
	v_max3_f32 v148, v148, v131, v132
	s_nop 0
	v_max3_f32 v146, v146, v125, v126
	v_max3_f32 v148, v148, v133, v138
	s_nop 0
	v_max3_f32 v146, v146, v127, v128
	v_max3_f32 v148, v148, v139, v140
	s_nop 0
	v_max3_f32 v146, v146, v129, v146
	v_max3_f32 v148, v148, v141, v148
	v_mov_b32_e32 v147, v146
	v_mov_b32_e32 v149, v148
	s_nop 1
	v_permlane16_swap_b32_e32 v146, v147
	v_permlane16_swap_b32_e32 v148, v149
	v_max_f32_e32 v146, v146, v147
	v_max_f32_e32 v148, v148, v149
	v_mov_b32_e32 v147, v146
	v_mov_b32_e32 v149, v148
	s_nop 1
	v_permlane32_swap_b32_e32 v146, v147
	v_permlane32_swap_b32_e32 v148, v149
	v_max_f32_e32 v147, v146, v147
	v_max_f32_e32 v146, v148, v149
	s_nop 0
	v_max_f32_e32 v148, v146, v146
	v_max_f32_e32 v149, v147, v147
	v_max_f32_e32 v150, v149, v148
	v_cmp_lt_f32_e32 vcc, s16, v150
	s_cbranch_vccz .Lat0_B652
	s_mov_b32 s15, 0xe0ad78ec
	v_max_f32_e32 v182, 0, v149
	v_cmp_ngt_f32_e32 vcc, s15, v147
	s_nop 1
	v_cndmask_b32_e32 v182, 0, v182, vcc
	v_max_f32_e32 v183, 0, v148
	v_cmp_ngt_f32_e32 vcc, s15, v146
	s_nop 1
	v_cndmask_b32_e32 v183, 0, v183, vcc
	v_exp_f32_e64 v184, -v182
	v_exp_f32_e64 v185, -v183
	v_add_f32_e32 v173, v173, v182
	v_add_f32_e32 v172, v172, v183
	v_mul_f32_e32 v175, v175, v184
	v_mul_f32_e32 v174, v174, v185
	v_sub_f32_e32 v114, v114, v182
	v_sub_f32_e32 v115, v115, v182
	v_sub_f32_e32 v116, v116, v182
	v_sub_f32_e32 v117, v117, v182
	v_sub_f32_e32 v118, v118, v182
	v_sub_f32_e32 v119, v119, v182
	v_sub_f32_e32 v120, v120, v182
	v_sub_f32_e32 v121, v121, v182
	v_sub_f32_e32 v122, v122, v182
	v_sub_f32_e32 v123, v123, v182
	v_sub_f32_e32 v124, v124, v182
	v_sub_f32_e32 v125, v125, v182
	v_sub_f32_e32 v126, v126, v182
	v_sub_f32_e32 v127, v127, v182
	v_sub_f32_e32 v128, v128, v182
	v_sub_f32_e32 v129, v129, v182
	v_sub_f32_e32 v134, v134, v183
	v_sub_f32_e32 v135, v135, v183
	v_sub_f32_e32 v136, v136, v183
	v_sub_f32_e32 v137, v137, v183
	v_sub_f32_e32 v142, v142, v183
	v_sub_f32_e32 v143, v143, v183
	v_sub_f32_e32 v144, v144, v183
	v_sub_f32_e32 v145, v145, v183
	v_sub_f32_e32 v130, v130, v183
	v_sub_f32_e32 v131, v131, v183
	v_sub_f32_e32 v132, v132, v183
	v_sub_f32_e32 v133, v133, v183
	v_sub_f32_e32 v138, v138, v183
	v_sub_f32_e32 v139, v139, v183
	v_sub_f32_e32 v140, v140, v183
	v_sub_f32_e32 v141, v141, v183
	v_pk_mul_f32 v[38:39], v[38:39], v[184:185] op_sel_hi:[1,0]
	v_pk_mul_f32 v[40:41], v[40:41], v[184:185] op_sel_hi:[1,0]
	v_pk_mul_f32 v[34:35], v[34:35], v[184:185] op_sel_hi:[1,0]
	v_pk_mul_f32 v[36:37], v[36:37], v[184:185] op_sel_hi:[1,0]
	v_pk_mul_f32 v[42:43], v[42:43], v[184:185] op_sel_hi:[1,0]
	v_pk_mul_f32 v[44:45], v[44:45], v[184:185] op_sel_hi:[1,0]
	v_pk_mul_f32 v[50:51], v[50:51], v[184:185] op_sel_hi:[1,0]
	v_pk_mul_f32 v[52:53], v[52:53], v[184:185] op_sel_hi:[1,0]
	v_pk_mul_f32 v[62:63], v[62:63], v[184:185] op_sel_hi:[1,0]
	v_pk_mul_f32 v[64:65], v[64:65], v[184:185] op_sel_hi:[1,0]
	v_pk_mul_f32 v[58:59], v[58:59], v[184:185] op_sel_hi:[1,0]
	v_pk_mul_f32 v[60:61], v[60:61], v[184:185] op_sel_hi:[1,0]
	v_pk_mul_f32 v[66:67], v[66:67], v[184:185] op_sel_hi:[1,0]
	v_pk_mul_f32 v[68:69], v[68:69], v[184:185] op_sel_hi:[1,0]
	v_pk_mul_f32 v[106:107], v[106:107], v[184:185] op_sel_hi:[1,0]
	v_pk_mul_f32 v[108:109], v[108:109], v[184:185] op_sel_hi:[1,0]
	v_pk_mul_f32 v[78:79], v[78:79], v[184:185] op_sel:[0,1] op_sel_hi:[1,1]
	v_pk_mul_f32 v[80:81], v[80:81], v[184:185] op_sel:[0,1] op_sel_hi:[1,1]
	v_pk_mul_f32 v[74:75], v[74:75], v[184:185] op_sel:[0,1] op_sel_hi:[1,1]
	v_pk_mul_f32 v[76:77], v[76:77], v[184:185] op_sel:[0,1] op_sel_hi:[1,1]
	v_pk_mul_f32 v[82:83], v[82:83], v[184:185] op_sel:[0,1] op_sel_hi:[1,1]
	v_pk_mul_f32 v[84:85], v[84:85], v[184:185] op_sel:[0,1] op_sel_hi:[1,1]
	v_pk_mul_f32 v[86:87], v[86:87], v[184:185] op_sel:[0,1] op_sel_hi:[1,1]
	v_pk_mul_f32 v[88:89], v[88:89], v[184:185] op_sel:[0,1] op_sel_hi:[1,1]
	v_pk_mul_f32 v[94:95], v[94:95], v[184:185] op_sel:[0,1] op_sel_hi:[1,1]
	v_pk_mul_f32 v[96:97], v[96:97], v[184:185] op_sel:[0,1] op_sel_hi:[1,1]
	v_pk_mul_f32 v[90:91], v[90:91], v[184:185] op_sel:[0,1] op_sel_hi:[1,1]
	v_pk_mul_f32 v[92:93], v[92:93], v[184:185] op_sel:[0,1] op_sel_hi:[1,1]
	v_pk_mul_f32 v[102:103], v[102:103], v[184:185] op_sel:[0,1] op_sel_hi:[1,1]
	v_pk_mul_f32 v[104:105], v[104:105], v[184:185] op_sel:[0,1] op_sel_hi:[1,1]
	v_pk_mul_f32 v[110:111], v[110:111], v[184:185] op_sel:[0,1] op_sel_hi:[1,1]
	v_pk_mul_f32 v[112:113], v[112:113], v[184:185] op_sel:[0,1] op_sel_hi:[1,1]
; __device__ __forceinline__ unsigned pk2(float lo, float hi) { unsigned r; asm volatile("v_cvt_pk_bf16_f32 %0, %1, %2" : "=v"(r) : "v"(lo), "v"(hi)); return r; }
; __device__ __forceinline__ float ex2(float x) { return __builtin_amdgcn_exp2f(x); }
; template <int NS, int DV, class MaskF> ...
;     ...
;     {
;         bf16x8 pkn[NS][2];
; #pragma unroll
;         for (int st = 0; st < NS; ++st) {
;             float ps = 0.f;
; #pragma unroll
;             for (int kt = 0; kt < 4; ++kt)
; #pragma unroll
;                 for (int i = 0; i < 4; ++i) { const float p = ex2(s[st][kt][i]); ps += p; s[st][kt][i] = p; }
;             lrun[st] += ps;
; #pragma unroll
;             for (int j = 0; j < 2; ++j) {
;                 u32x4 w; w.x = pk2(s[st][2 * j][0], s[st][2 * j][1]); w.y = pk2(s[st][2 * j][2], s[st][2 * j][3]);
;                 w.z = pk2(s[st][2 * j + 1][0], s[st][2 * j + 1][1]); w.w = pk2(s[st][2 * j + 1][2], s[st][2 * j + 1][3]);
;                 pkn[st][j] = __builtin_bit_cast(bf16x8, w);
;             }
;         }
;     ...
;         for (int st = 0; st < NS; ++st) { pkp[st][0] = pkn[st][0]; pkp[st][1] = pkn[st][1]; }
; template <int MODE>
; __device__ __forceinline__ void attn_unit(const Params& p, int layer, LAS unsigned char* lds, int b, int hsel, int qb, bool ctxq) {
;     ...
;         bprev = bcur; bcur = bnext;
;         __syncthreads();
;     }
.Lat0_B652:
	v_exp_f32_e32 v71, v114
	v_exp_f32_e32 v70, v134
	v_exp_f32_e32 v73, v115
	v_exp_f32_e32 v72, v135
	v_exp_f32_e32 v101, v116
	v_exp_f32_e32 v100, v136
	v_exp_f32_e32 v115, v117
	v_exp_f32_e32 v114, v137
	v_exp_f32_e32 v117, v118
	v_exp_f32_e32 v116, v142
	v_pk_add_f32 v[98:99], v[70:71], 0 op_sel_hi:[1,0]
	v_exp_f32_e32 v119, v119
	v_exp_f32_e32 v118, v143
	v_pk_add_f32 v[98:99], v[72:73], v[98:99]
	v_exp_f32_e32 v183, v120
	v_exp_f32_e32 v182, v144
	v_pk_add_f32 v[98:99], v[100:101], v[98:99]
	v_exp_f32_e32 v121, v121
	v_exp_f32_e32 v120, v145
	v_pk_add_f32 v[98:99], v[114:115], v[98:99]
	v_exp_f32_e32 v185, v122
	v_pk_add_f32 v[98:99], v[116:117], v[98:99]
	v_exp_f32_e32 v184, v130
	v_exp_f32_e32 v123, v123
	v_pk_add_f32 v[98:99], v[118:119], v[98:99]
	v_exp_f32_e32 v122, v131
	v_exp_f32_e32 v187, v124
	v_pk_add_f32 v[98:99], v[182:183], v[98:99]
	v_exp_f32_e32 v186, v132
	v_exp_f32_e32 v125, v125
	v_pk_add_f32 v[98:99], v[120:121], v[98:99]
	v_exp_f32_e32 v124, v133
	v_exp_f32_e32 v189, v126
	v_exp_f32_e32 v188, v138
	v_pk_add_f32 v[98:99], v[184:185], v[98:99]
	v_exp_f32_e32 v127, v127
	v_exp_f32_e32 v126, v139
	v_pk_add_f32 v[98:99], v[122:123], v[98:99]
	v_exp_f32_e32 v191, v128
	v_exp_f32_e32 v190, v140
	v_pk_add_f32 v[98:99], v[186:187], v[98:99]
	v_exp_f32_e32 v129, v129
	v_exp_f32_e32 v128, v141
	v_pk_add_f32 v[98:99], v[124:125], v[98:99]
	v_cvt_pk_bf16_f32 v54, v71, v73
	v_cvt_pk_bf16_f32 v55, v101, v115
	v_cvt_pk_bf16_f32 v56, v117, v119
	v_cvt_pk_bf16_f32 v57, v183, v121
	v_cvt_pk_bf16_f32 v46, v185, v123
	s_nop 0
	v_pk_add_f32 v[98:99], v[188:189], v[98:99]
	v_cvt_pk_bf16_f32 v47, v187, v125
	v_cvt_pk_bf16_f32 v48, v189, v127
	v_cvt_pk_bf16_f32 v49, v191, v129
	s_nop 0
	v_pk_add_f32 v[98:99], v[126:127], v[98:99]
	s_nop 0
	v_pk_add_f32 v[98:99], v[190:191], v[98:99]
	s_nop 0
	v_pk_add_f32 v[98:99], v[128:129], v[98:99]
	s_nop 0
	v_pk_add_f32 v[174:175], v[98:99], v[174:175]
	v_cvt_pk_bf16_f32 v98, v70, v72
	v_cvt_pk_bf16_f32 v99, v100, v114
	v_cvt_pk_bf16_f32 v100, v116, v118
	v_cvt_pk_bf16_f32 v101, v182, v120
	v_cvt_pk_bf16_f32 v70, v184, v122
	v_cvt_pk_bf16_f32 v71, v186, v124
	v_cvt_pk_bf16_f32 v72, v188, v126
	v_cvt_pk_bf16_f32 v73, v190, v128
	s_add_i32 s0, s0, 64
	s_add_i32 s12, s12, 1
	s_mov_b64 s[16:17], 0x80
	s_cmpk_lg_i32 s0, 0x20c0
	v_lshl_add_u64 v[176:177], v[176:177], 0, s[16:17]
	s_barrier
	s_cbranch_scc0 .LBB0_641
	s_mov_b32 s15, s13
	s_branch .LBB0_646
